# v36 + nt on the in-proj epilogue bf16 stores (q / kv outputs)
# speedup vs baseline: 1.0197x; 1.0197x over previous
; __device__ __forceinline__ u32x2 pack4(f32x4 v) { u32x2 w; w.x = cvtpk(v[0], v[1]); w.y = cvtpk(v[2], v[3]); return w; }
;     __device__ __forceinline__ void operator()(const Acc& acc, const Unit& u, int wr, int wc, int fr, int fq) const {
;     ...
;                     const int row = rowb + ai * 128 + m * 16;
;                     f32x4 v[2][2];
; #pragma unroll
;                     for (int bj = 0; bj < 2; ++bj) { v[bj][0] = acc[ai][bj][m][0]; v[bj][1] = acc[ai][bj][m][1]; }
;                     if (rope) { const f32x4 cs = *(const f32x4*)(ropeP + (size_t)row * 32 + 4 * fq), sn = *(const f32x4*)(ropeP + (size_t)row * 32 + 16 + 4 * fq);
; #pragma unroll
;                         for (int bj = 0; bj < 2; ++bj) { const f32x4 x1 = v[bj][0], x2 = v[bj][1]; v[bj][0] = x1 * cs - x2 * sn; v[bj][1] = x2 * cs + x1 * sn; } }
;                     bf16_t* rp = dst + (size_t)row * ldo + wc * 32 + 4 * fq;
; #pragma unroll
;                     for (int bj = 0; bj < 2; ++bj)
; #pragma unroll
;                         for (int n = 0; n < 2; ++n) *(u32x2*)(rp + bj * 128 + n * 16) = pack4(v[bj][n]);
.LBB0_495:
	v_mad_i64_i32 v[2:3], s[4:5], s6, v2, 0
	v_lshl_add_u64 v[2:3], v[2:3], 1, v[6:7]
	v_cvt_pk_bf16_f32 v4, v46, v47
	s_waitcnt lgkmcnt(0)
	v_cvt_pk_bf16_f32 v5, v48, v49
	global_store_dwordx2 v[2:3], v[4:5], off nt
	v_cvt_pk_bf16_f32 v4, v42, v43
	v_cvt_pk_bf16_f32 v5, v44, v45
	global_store_dwordx2 v[2:3], v[4:5], off offset:32 nt
	v_cvt_pk_bf16_f32 v4, v38, v39
	v_cvt_pk_bf16_f32 v5, v40, v41
	global_store_dwordx2 v[2:3], v[4:5], off offset:256 nt
	v_cvt_pk_bf16_f32 v4, v34, v35
	v_cvt_pk_bf16_f32 v5, v36, v37
	global_store_dwordx2 v[2:3], v[4:5], off offset:288 nt

; __device__ __forceinline__ u32x2 pack4(f32x4 v) { u32x2 w; w.x = cvtpk(v[0], v[1]); w.y = cvtpk(v[2], v[3]); return w; }
;     __device__ __forceinline__ void operator()(const Acc& acc, const Unit& u, int wr, int wc, int fr, int fq) const {
;     ...
;                 for (int m = 0; m < 4; ++m) {
;                     const int row = rowb + ai * 128 + m * 16;
;                     f32x4 v[2][2];
; #pragma unroll
;                     for (int bj = 0; bj < 2; ++bj) { v[bj][0] = acc[ai][bj][m][0]; v[bj][1] = acc[ai][bj][m][1]; }
;                     if (rope) { const f32x4 cs = *(const f32x4*)(ropeP + (size_t)row * 32 + 4 * fq), sn = *(const f32x4*)(ropeP + (size_t)row * 32 + 16 + 4 * fq);
; #pragma unroll
;                         for (int bj = 0; bj < 2; ++bj) { const f32x4 x1 = v[bj][0], x2 = v[bj][1]; v[bj][0] = x1 * cs - x2 * sn; v[bj][1] = x2 * cs + x1 * sn; } }
;                     bf16_t* rp = dst + (size_t)row * ldo + wc * 32 + 4 * fq;
; #pragma unroll
;                     for (int bj = 0; bj < 2; ++bj)
; #pragma unroll
;                         for (int n = 0; n < 2; ++n) *(u32x2*)(rp + bj * 128 + n * 16) = pack4(v[bj][n]);
.LBB0_550:
	s_lshl_b32 s7, s65, 1
	s_add_u32 s46, s46, s7
	s_addc_u32 s47, s47, 0
	v_lshlrev_b32_e32 v166, 1, v166
	v_lshl_add_u64 v[6:7], s[46:47], 0, v[166:167]
	v_mad_i64_i32 v[8:9], s[46:47], s6, v2, 0
	v_lshl_add_u64 v[8:9], v[8:9], 1, v[6:7]
	v_cvt_pk_bf16_f32 v10, v158, v159
	v_cvt_pk_bf16_f32 v11, v160, v161
	global_store_dwordx2 v[8:9], v[10:11], off nt
	v_cvt_pk_bf16_f32 v10, v154, v155
	v_cvt_pk_bf16_f32 v11, v156, v157
	global_store_dwordx2 v[8:9], v[10:11], off offset:32 nt
	v_cvt_pk_bf16_f32 v10, v150, v151
	v_cvt_pk_bf16_f32 v11, v152, v153
	global_store_dwordx2 v[8:9], v[10:11], off offset:256 nt
	v_cvt_pk_bf16_f32 v10, v146, v147
	v_cvt_pk_bf16_f32 v11, v148, v149
	global_store_dwordx2 v[8:9], v[10:11], off offset:288 nt
	v_or_b32_e32 v8, 16, v2
	s_and_b64 vcc, exec, s[4:5]
	v_ashrrev_i32_e32 v9, 31, v8
	s_cbranch_vccnz .LBB0_552
	v_lshlrev_b64 v[10:11], 7, v[8:9]
	v_lshl_add_u64 v[10:11], s[20:21], 0, v[10:11]
	s_waitcnt lgkmcnt(0)
	v_mov_b32_e32 v5, v167
	v_lshl_add_u64 v[14:15], v[10:11], 0, v[4:5]
	global_load_dwordx4 v[10:13], v[14:15], off offset:64
	s_nop 0
	global_load_dwordx4 v[14:17], v[14:15], off
	s_waitcnt vmcnt(0)
	v_pk_mul_f32 v[18:19], v[140:141], v[12:13]
	v_pk_mul_f32 v[20:21], v[138:139], v[10:11]
	v_pk_mul_f32 v[22:23], v[144:145], v[12:13]
	v_pk_mul_f32 v[24:25], v[142:143], v[10:11]
	v_pk_mul_f32 v[26:27], v[132:133], v[12:13]
	v_pk_mul_f32 v[28:29], v[130:131], v[10:11]
	v_pk_mul_f32 v[12:13], v[136:137], v[12:13]
	v_pk_mul_f32 v[10:11], v[134:135], v[10:11]
	v_pk_fma_f32 v[144:145], v[144:145], v[16:17], v[18:19] neg_lo:[0,0,1] neg_hi:[0,0,1]
	v_pk_fma_f32 v[142:143], v[142:143], v[14:15], v[20:21] neg_lo:[0,0,1] neg_hi:[0,0,1]
	v_pk_fma_f32 v[140:141], v[140:141], v[16:17], v[22:23]
	v_pk_fma_f32 v[138:139], v[138:139], v[14:15], v[24:25]
	v_pk_fma_f32 v[136:137], v[136:137], v[16:17], v[26:27] neg_lo:[0,0,1] neg_hi:[0,0,1]
	v_pk_fma_f32 v[134:135], v[134:135], v[14:15], v[28:29] neg_lo:[0,0,1] neg_hi:[0,0,1]
	v_pk_fma_f32 v[132:133], v[132:133], v[16:17], v[12:13]
	v_pk_fma_f32 v[130:131], v[130:131], v[14:15], v[10:11]
.LBB0_552:
	v_mad_i64_i32 v[8:9], s[46:47], s6, v8, 0
	v_lshl_add_u64 v[8:9], v[8:9], 1, v[6:7]
	v_cvt_pk_bf16_f32 v10, v142, v143
	v_cvt_pk_bf16_f32 v11, v144, v145
	global_store_dwordx2 v[8:9], v[10:11], off nt
	v_cvt_pk_bf16_f32 v10, v138, v139
	v_cvt_pk_bf16_f32 v11, v140, v141
	global_store_dwordx2 v[8:9], v[10:11], off offset:32 nt
	v_cvt_pk_bf16_f32 v10, v134, v135
	v_cvt_pk_bf16_f32 v11, v136, v137
	global_store_dwordx2 v[8:9], v[10:11], off offset:256 nt
	v_cvt_pk_bf16_f32 v10, v130, v131
	v_cvt_pk_bf16_f32 v11, v132, v133
	global_store_dwordx2 v[8:9], v[10:11], off offset:288 nt
	v_or_b32_e32 v8, 32, v2
	s_and_b64 vcc, exec, s[4:5]
	v_ashrrev_i32_e32 v9, 31, v8
	s_cbranch_vccnz .LBB0_554
	v_lshlrev_b64 v[10:11], 7, v[8:9]
	v_lshl_add_u64 v[10:11], s[20:21], 0, v[10:11]
	s_waitcnt lgkmcnt(0)
	v_mov_b32_e32 v5, v167
	v_lshl_add_u64 v[14:15], v[10:11], 0, v[4:5]
	global_load_dwordx4 v[10:13], v[14:15], off offset:64
	s_nop 0
	global_load_dwordx4 v[14:17], v[14:15], off
	s_waitcnt vmcnt(0)
	v_pk_mul_f32 v[18:19], v[124:125], v[12:13]
	v_pk_mul_f32 v[20:21], v[122:123], v[10:11]
	v_pk_mul_f32 v[22:23], v[128:129], v[12:13]
	v_pk_mul_f32 v[24:25], v[126:127], v[10:11]
	v_pk_mul_f32 v[26:27], v[116:117], v[12:13]
	v_pk_mul_f32 v[28:29], v[114:115], v[10:11]
	v_pk_mul_f32 v[12:13], v[120:121], v[12:13]
	v_pk_mul_f32 v[10:11], v[118:119], v[10:11]
	v_pk_fma_f32 v[128:129], v[128:129], v[16:17], v[18:19] neg_lo:[0,0,1] neg_hi:[0,0,1]
	v_pk_fma_f32 v[126:127], v[126:127], v[14:15], v[20:21] neg_lo:[0,0,1] neg_hi:[0,0,1]
	v_pk_fma_f32 v[124:125], v[124:125], v[16:17], v[22:23]
	v_pk_fma_f32 v[122:123], v[122:123], v[14:15], v[24:25]
	v_pk_fma_f32 v[120:121], v[120:121], v[16:17], v[26:27] neg_lo:[0,0,1] neg_hi:[0,0,1]
	v_pk_fma_f32 v[118:119], v[118:119], v[14:15], v[28:29] neg_lo:[0,0,1] neg_hi:[0,0,1]
	v_pk_fma_f32 v[116:117], v[116:117], v[16:17], v[12:13]
	v_pk_fma_f32 v[114:115], v[114:115], v[14:15], v[10:11]
.LBB0_554:
	v_mad_i64_i32 v[8:9], s[46:47], s6, v8, 0
	v_lshl_add_u64 v[8:9], v[8:9], 1, v[6:7]
	v_cvt_pk_bf16_f32 v10, v126, v127
	v_cvt_pk_bf16_f32 v11, v128, v129
	global_store_dwordx2 v[8:9], v[10:11], off nt
	v_cvt_pk_bf16_f32 v10, v122, v123
	v_cvt_pk_bf16_f32 v11, v124, v125
	global_store_dwordx2 v[8:9], v[10:11], off offset:32 nt
	v_cvt_pk_bf16_f32 v10, v118, v119
	v_cvt_pk_bf16_f32 v11, v120, v121
	global_store_dwordx2 v[8:9], v[10:11], off offset:256 nt
	v_cvt_pk_bf16_f32 v10, v114, v115
	v_cvt_pk_bf16_f32 v11, v116, v117
	global_store_dwordx2 v[8:9], v[10:11], off offset:288 nt
	v_or_b32_e32 v8, 48, v2
	s_and_b64 vcc, exec, s[4:5]
	v_ashrrev_i32_e32 v9, 31, v8
	s_cbranch_vccnz .LBB0_556
	v_lshlrev_b64 v[10:11], 7, v[8:9]
	v_lshl_add_u64 v[10:11], s[20:21], 0, v[10:11]
	s_waitcnt lgkmcnt(0)
	v_mov_b32_e32 v5, v167
	v_lshl_add_u64 v[14:15], v[10:11], 0, v[4:5]
	global_load_dwordx4 v[10:13], v[14:15], off offset:64
	s_nop 0
	global_load_dwordx4 v[14:17], v[14:15], off
	s_waitcnt vmcnt(0)
	v_pk_mul_f32 v[18:19], v[108:109], v[12:13]
	v_pk_mul_f32 v[20:21], v[106:107], v[10:11]
	v_pk_mul_f32 v[22:23], v[112:113], v[12:13]
	v_pk_mul_f32 v[24:25], v[110:111], v[10:11]
	v_pk_mul_f32 v[26:27], v[100:101], v[12:13]
	v_pk_mul_f32 v[28:29], v[98:99], v[10:11]
	v_pk_mul_f32 v[12:13], v[104:105], v[12:13]
	v_pk_mul_f32 v[10:11], v[102:103], v[10:11]
	v_pk_fma_f32 v[112:113], v[112:113], v[16:17], v[18:19] neg_lo:[0,0,1] neg_hi:[0,0,1]
	v_pk_fma_f32 v[110:111], v[110:111], v[14:15], v[20:21] neg_lo:[0,0,1] neg_hi:[0,0,1]
	v_pk_fma_f32 v[108:109], v[108:109], v[16:17], v[22:23]
	v_pk_fma_f32 v[106:107], v[106:107], v[14:15], v[24:25]
	v_pk_fma_f32 v[104:105], v[104:105], v[16:17], v[26:27] neg_lo:[0,0,1] neg_hi:[0,0,1]
	v_pk_fma_f32 v[102:103], v[102:103], v[14:15], v[28:29] neg_lo:[0,0,1] neg_hi:[0,0,1]
	v_pk_fma_f32 v[100:101], v[100:101], v[16:17], v[12:13]
	v_pk_fma_f32 v[98:99], v[98:99], v[14:15], v[10:11]
; __device__ __forceinline__ u32x2 pack4(f32x4 v) { u32x2 w; w.x = cvtpk(v[0], v[1]); w.y = cvtpk(v[2], v[3]); return w; }
;     __device__ __forceinline__ void operator()(const Acc& acc, const Unit& u, int wr, int wc, int fr, int fq) const {
;     ...
;                 for (int m = 0; m < 4; ++m) {
;                     const int row = rowb + ai * 128 + m * 16;
;                     f32x4 v[2][2];
; #pragma unroll
;                     for (int bj = 0; bj < 2; ++bj) { v[bj][0] = acc[ai][bj][m][0]; v[bj][1] = acc[ai][bj][m][1]; }
;                     if (rope) { const f32x4 cs = *(const f32x4*)(ropeP + (size_t)row * 32 + 4 * fq), sn = *(const f32x4*)(ropeP + (size_t)row * 32 + 16 + 4 * fq);
; #pragma unroll
;                         for (int bj = 0; bj < 2; ++bj) { const f32x4 x1 = v[bj][0], x2 = v[bj][1]; v[bj][0] = x1 * cs - x2 * sn; v[bj][1] = x2 * cs + x1 * sn; } }
;                     bf16_t* rp = dst + (size_t)row * ldo + wc * 32 + 4 * fq;
; #pragma unroll
;                     for (int bj = 0; bj < 2; ++bj)
; #pragma unroll
;                         for (int n = 0; n < 2; ++n) *(u32x2*)(rp + bj * 128 + n * 16) = pack4(v[bj][n]);
.LBB0_556:
	v_mad_i64_i32 v[8:9], s[46:47], s6, v8, 0
	v_lshl_add_u64 v[8:9], v[8:9], 1, v[6:7]
	v_cvt_pk_bf16_f32 v10, v110, v111
	v_cvt_pk_bf16_f32 v11, v112, v113
	global_store_dwordx2 v[8:9], v[10:11], off nt
	v_cvt_pk_bf16_f32 v10, v106, v107
	v_cvt_pk_bf16_f32 v11, v108, v109
	global_store_dwordx2 v[8:9], v[10:11], off offset:32 nt
	v_cvt_pk_bf16_f32 v10, v102, v103
	v_cvt_pk_bf16_f32 v11, v104, v105
	global_store_dwordx2 v[8:9], v[10:11], off offset:256 nt
	v_cvt_pk_bf16_f32 v10, v98, v99
	v_cvt_pk_bf16_f32 v11, v100, v101
	global_store_dwordx2 v[8:9], v[10:11], off offset:288 nt
	v_add_u32_e32 v8, 0x80, v2
	s_and_b64 vcc, exec, s[4:5]
	v_ashrrev_i32_e32 v9, 31, v8
	s_cbranch_vccnz .LBB0_558
	v_lshlrev_b64 v[10:11], 7, v[8:9]
	v_lshl_add_u64 v[10:11], s[20:21], 0, v[10:11]
	s_waitcnt lgkmcnt(0)
	v_mov_b32_e32 v5, v167
	v_lshl_add_u64 v[14:15], v[10:11], 0, v[4:5]
	global_load_dwordx4 v[10:13], v[14:15], off offset:64
	s_nop 0
	global_load_dwordx4 v[14:17], v[14:15], off
	s_waitcnt vmcnt(0)
	v_pk_mul_f32 v[18:19], v[92:93], v[12:13]
	v_pk_mul_f32 v[20:21], v[90:91], v[10:11]
	v_pk_mul_f32 v[22:23], v[96:97], v[12:13]
	v_pk_mul_f32 v[24:25], v[94:95], v[10:11]
	v_pk_mul_f32 v[26:27], v[84:85], v[12:13]
	v_pk_mul_f32 v[28:29], v[82:83], v[10:11]
	v_pk_mul_f32 v[12:13], v[88:89], v[12:13]
	v_pk_mul_f32 v[10:11], v[86:87], v[10:11]
	v_pk_fma_f32 v[96:97], v[96:97], v[16:17], v[18:19] neg_lo:[0,0,1] neg_hi:[0,0,1]
	v_pk_fma_f32 v[94:95], v[94:95], v[14:15], v[20:21] neg_lo:[0,0,1] neg_hi:[0,0,1]
	v_pk_fma_f32 v[92:93], v[92:93], v[16:17], v[22:23]
	v_pk_fma_f32 v[90:91], v[90:91], v[14:15], v[24:25]
	v_pk_fma_f32 v[88:89], v[88:89], v[16:17], v[26:27] neg_lo:[0,0,1] neg_hi:[0,0,1]
	v_pk_fma_f32 v[86:87], v[86:87], v[14:15], v[28:29] neg_lo:[0,0,1] neg_hi:[0,0,1]
	v_pk_fma_f32 v[84:85], v[84:85], v[16:17], v[12:13]
	v_pk_fma_f32 v[82:83], v[82:83], v[14:15], v[10:11]
.LBB0_558:
	v_mad_i64_i32 v[8:9], s[46:47], s6, v8, 0
	v_lshl_add_u64 v[8:9], v[8:9], 1, v[6:7]
	v_cvt_pk_bf16_f32 v10, v94, v95
	v_cvt_pk_bf16_f32 v11, v96, v97
	global_store_dwordx2 v[8:9], v[10:11], off nt
	v_cvt_pk_bf16_f32 v10, v90, v91
	v_cvt_pk_bf16_f32 v11, v92, v93
	global_store_dwordx2 v[8:9], v[10:11], off offset:32 nt
	v_cvt_pk_bf16_f32 v10, v86, v87
	v_cvt_pk_bf16_f32 v11, v88, v89
	global_store_dwordx2 v[8:9], v[10:11], off offset:256 nt
	v_cvt_pk_bf16_f32 v10, v82, v83
	v_cvt_pk_bf16_f32 v11, v84, v85
	global_store_dwordx2 v[8:9], v[10:11], off offset:288 nt
	v_add_u32_e32 v8, 0x90, v2
	s_and_b64 vcc, exec, s[4:5]
	v_ashrrev_i32_e32 v9, 31, v8
	s_cbranch_vccnz .LBB0_560
	v_lshlrev_b64 v[10:11], 7, v[8:9]
	v_lshl_add_u64 v[10:11], s[20:21], 0, v[10:11]
	s_waitcnt lgkmcnt(0)
	v_mov_b32_e32 v5, v167
	v_lshl_add_u64 v[14:15], v[10:11], 0, v[4:5]
	global_load_dwordx4 v[10:13], v[14:15], off offset:64
	s_nop 0
	global_load_dwordx4 v[14:17], v[14:15], off
	s_waitcnt vmcnt(0)
	v_pk_mul_f32 v[18:19], v[76:77], v[12:13]
	v_pk_mul_f32 v[20:21], v[74:75], v[10:11]
	v_pk_mul_f32 v[22:23], v[80:81], v[12:13]
	v_pk_mul_f32 v[24:25], v[78:79], v[10:11]
	v_pk_mul_f32 v[26:27], v[68:69], v[12:13]
	v_pk_mul_f32 v[28:29], v[66:67], v[10:11]
	v_pk_mul_f32 v[12:13], v[72:73], v[12:13]
	v_pk_mul_f32 v[10:11], v[70:71], v[10:11]
	v_pk_fma_f32 v[80:81], v[80:81], v[16:17], v[18:19] neg_lo:[0,0,1] neg_hi:[0,0,1]
	v_pk_fma_f32 v[78:79], v[78:79], v[14:15], v[20:21] neg_lo:[0,0,1] neg_hi:[0,0,1]
	v_pk_fma_f32 v[76:77], v[76:77], v[16:17], v[22:23]
	v_pk_fma_f32 v[74:75], v[74:75], v[14:15], v[24:25]
	v_pk_fma_f32 v[72:73], v[72:73], v[16:17], v[26:27] neg_lo:[0,0,1] neg_hi:[0,0,1]
	v_pk_fma_f32 v[70:71], v[70:71], v[14:15], v[28:29] neg_lo:[0,0,1] neg_hi:[0,0,1]
	v_pk_fma_f32 v[68:69], v[68:69], v[16:17], v[12:13]
	v_pk_fma_f32 v[66:67], v[66:67], v[14:15], v[10:11]
; __device__ __forceinline__ u32x2 pack4(f32x4 v) { u32x2 w; w.x = cvtpk(v[0], v[1]); w.y = cvtpk(v[2], v[3]); return w; }
;     __device__ __forceinline__ void operator()(const Acc& acc, const Unit& u, int wr, int wc, int fr, int fq) const {
;     ...
;                 for (int m = 0; m < 4; ++m) {
;                     const int row = rowb + ai * 128 + m * 16;
;                     f32x4 v[2][2];
; #pragma unroll
;                     for (int bj = 0; bj < 2; ++bj) { v[bj][0] = acc[ai][bj][m][0]; v[bj][1] = acc[ai][bj][m][1]; }
;                     if (rope) { const f32x4 cs = *(const f32x4*)(ropeP + (size_t)row * 32 + 4 * fq), sn = *(const f32x4*)(ropeP + (size_t)row * 32 + 16 + 4 * fq);
; #pragma unroll
;                         for (int bj = 0; bj < 2; ++bj) { const f32x4 x1 = v[bj][0], x2 = v[bj][1]; v[bj][0] = x1 * cs - x2 * sn; v[bj][1] = x2 * cs + x1 * sn; } }
;                     bf16_t* rp = dst + (size_t)row * ldo + wc * 32 + 4 * fq;
; #pragma unroll
;                     for (int bj = 0; bj < 2; ++bj)
; #pragma unroll
;                         for (int n = 0; n < 2; ++n) *(u32x2*)(rp + bj * 128 + n * 16) = pack4(v[bj][n]);
.LBB0_560:
	v_mad_i64_i32 v[8:9], s[46:47], s6, v8, 0
	v_lshl_add_u64 v[8:9], v[8:9], 1, v[6:7]
	v_cvt_pk_bf16_f32 v10, v78, v79
	v_cvt_pk_bf16_f32 v11, v80, v81
	global_store_dwordx2 v[8:9], v[10:11], off nt
	v_cvt_pk_bf16_f32 v10, v74, v75
	v_cvt_pk_bf16_f32 v11, v76, v77
	global_store_dwordx2 v[8:9], v[10:11], off offset:32 nt
	v_cvt_pk_bf16_f32 v10, v70, v71
	v_cvt_pk_bf16_f32 v11, v72, v73
	global_store_dwordx2 v[8:9], v[10:11], off offset:256 nt
	v_cvt_pk_bf16_f32 v10, v66, v67
	v_cvt_pk_bf16_f32 v11, v68, v69
	global_store_dwordx2 v[8:9], v[10:11], off offset:288 nt
	v_add_u32_e32 v8, 0xa0, v2
	s_and_b64 vcc, exec, s[4:5]
	v_ashrrev_i32_e32 v9, 31, v8
	s_cbranch_vccnz .LBB0_562
	v_lshlrev_b64 v[10:11], 7, v[8:9]
	v_lshl_add_u64 v[10:11], s[20:21], 0, v[10:11]
	s_waitcnt lgkmcnt(0)
	v_mov_b32_e32 v5, v167
	v_lshl_add_u64 v[14:15], v[10:11], 0, v[4:5]
	global_load_dwordx4 v[10:13], v[14:15], off offset:64
	s_nop 0
	global_load_dwordx4 v[14:17], v[14:15], off
	s_waitcnt vmcnt(0)
	v_pk_mul_f32 v[18:19], v[60:61], v[12:13]
	v_pk_mul_f32 v[20:21], v[58:59], v[10:11]
	v_pk_mul_f32 v[22:23], v[64:65], v[12:13]
	v_pk_mul_f32 v[24:25], v[62:63], v[10:11]
	v_pk_mul_f32 v[26:27], v[52:53], v[12:13]
	v_pk_mul_f32 v[28:29], v[50:51], v[10:11]
	v_pk_mul_f32 v[12:13], v[56:57], v[12:13]
	v_pk_mul_f32 v[10:11], v[54:55], v[10:11]
	v_pk_fma_f32 v[64:65], v[64:65], v[16:17], v[18:19] neg_lo:[0,0,1] neg_hi:[0,0,1]
	v_pk_fma_f32 v[62:63], v[62:63], v[14:15], v[20:21] neg_lo:[0,0,1] neg_hi:[0,0,1]
	v_pk_fma_f32 v[60:61], v[60:61], v[16:17], v[22:23]
	v_pk_fma_f32 v[58:59], v[58:59], v[14:15], v[24:25]
	v_pk_fma_f32 v[56:57], v[56:57], v[16:17], v[26:27] neg_lo:[0,0,1] neg_hi:[0,0,1]
	v_pk_fma_f32 v[54:55], v[54:55], v[14:15], v[28:29] neg_lo:[0,0,1] neg_hi:[0,0,1]
	v_pk_fma_f32 v[52:53], v[52:53], v[16:17], v[12:13]
	v_pk_fma_f32 v[50:51], v[50:51], v[14:15], v[10:11]
.LBB0_562:
	v_mad_i64_i32 v[8:9], s[46:47], s6, v8, 0
	v_lshl_add_u64 v[8:9], v[8:9], 1, v[6:7]
	v_cvt_pk_bf16_f32 v10, v62, v63
	v_cvt_pk_bf16_f32 v11, v64, v65
	global_store_dwordx2 v[8:9], v[10:11], off nt
	v_cvt_pk_bf16_f32 v10, v58, v59
	v_cvt_pk_bf16_f32 v11, v60, v61
	global_store_dwordx2 v[8:9], v[10:11], off offset:32 nt
	v_cvt_pk_bf16_f32 v10, v54, v55
	v_cvt_pk_bf16_f32 v11, v56, v57
	v_add_u32_e32 v2, 0xb0, v2
	global_store_dwordx2 v[8:9], v[10:11], off offset:256 nt
	v_cvt_pk_bf16_f32 v10, v50, v51
	v_cvt_pk_bf16_f32 v11, v52, v53
	s_and_b64 vcc, exec, s[4:5]
	v_ashrrev_i32_e32 v3, 31, v2
	global_store_dwordx2 v[8:9], v[10:11], off offset:288 nt
	s_cbranch_vccnz .LBB0_495
	v_lshlrev_b64 v[8:9], 7, v[2:3]
	v_lshl_add_u64 v[8:9], s[20:21], 0, v[8:9]
	s_waitcnt lgkmcnt(0)
	v_mov_b32_e32 v5, v167
	v_lshl_add_u64 v[4:5], v[8:9], 0, v[4:5]
	global_load_dwordx4 v[8:11], v[4:5], off offset:64
	global_load_dwordx4 v[12:15], v[4:5], off
	s_waitcnt vmcnt(0)
	v_pk_mul_f32 v[4:5], v[44:45], v[10:11]
	v_pk_mul_f32 v[16:17], v[42:43], v[8:9]
	v_pk_mul_f32 v[18:19], v[48:49], v[10:11]
	v_pk_mul_f32 v[20:21], v[46:47], v[8:9]
	v_pk_mul_f32 v[22:23], v[36:37], v[10:11]
	v_pk_mul_f32 v[24:25], v[34:35], v[8:9]
	v_pk_mul_f32 v[10:11], v[40:41], v[10:11]
	v_pk_mul_f32 v[8:9], v[38:39], v[8:9]
	v_pk_fma_f32 v[48:49], v[48:49], v[14:15], v[4:5] neg_lo:[0,0,1] neg_hi:[0,0,1]
	v_pk_fma_f32 v[46:47], v[46:47], v[12:13], v[16:17] neg_lo:[0,0,1] neg_hi:[0,0,1]
	v_pk_fma_f32 v[44:45], v[44:45], v[14:15], v[18:19]
	v_pk_fma_f32 v[42:43], v[42:43], v[12:13], v[20:21]
	v_pk_fma_f32 v[40:41], v[40:41], v[14:15], v[22:23] neg_lo:[0,0,1] neg_hi:[0,0,1]
	v_pk_fma_f32 v[38:39], v[38:39], v[12:13], v[24:25] neg_lo:[0,0,1] neg_hi:[0,0,1]
	v_pk_fma_f32 v[36:37], v[36:37], v[14:15], v[10:11]
	v_pk_fma_f32 v[34:35], v[34:35], v[12:13], v[8:9]
	s_branch .LBB0_495
